# v33: v26 with the softmax transcendentals re-spaced: one v_exp per QK MFMA gap (with its adds and pack) and two per PV gap instead of clusters of 2-3
# baseline (speedup 1.0000x reference)
.LBB0_526:
	ds_read_b128 v[64:67], v192 offset:49152
	ds_read_b128 v[68:71], v192 offset:57344
	ds_read_b128 v[232:235], v200 offset:49152
	ds_read_b128 v[236:239], v200 offset:57344
	ds_read_b128 v[250:253], v199 offset:49152
	ds_read_b128 v[244:247], v199 offset:57344
	ds_read_b128 v[212:215], v198 offset:49152
	ds_read_b128 v[216:219], v198 offset:57344
	v_add_f32_e32 v204, v163, v177
	v_exp_f32_e32 v160, v160
	v_exp_f32_e32 v161, v161
	s_waitcnt lgkmcnt(6)
	v_mfma_f32_32x32x16_bf16 v[80:95], v[64:67], v[118:121], 0
	v_exp_f32_e32 v158, v158
	v_add_f32_e32 v204, v164, v204
	v_add_f32_e32 v204, v207, v204
	v_cvt_pk_bf16_f32 v162, v163, v177
	v_mfma_f32_32x32x16_bf16 v[64:79], v[68:71], v[118:121], 0
	v_exp_f32_e32 v159, v159
	v_add_f32_e32 v204, v176, v204
	v_add_f32_e32 v204, v210, v204
	v_cvt_pk_bf16_f32 v163, v164, v207
	s_waitcnt lgkmcnt(4)
	v_mfma_f32_32x32x16_bf16 v[80:95], v[232:235], v[114:117], v[80:95]
	ds_read_b128 v[232:235], v195 offset:49152
	v_exp_f32_e32 v154, v154
	v_add_f32_e32 v204, v165, v204
	v_add_f32_e32 v204, v175, v204
	v_cvt_pk_bf16_f32 v164, v176, v210
	v_mfma_f32_32x32x16_bf16 v[64:79], v[236:239], v[114:117], v[64:79]
	ds_read_b128 v[236:239], v195 offset:57344
	v_exp_f32_e32 v155, v155
	v_add_f32_e32 v204, v166, v204
	v_add_f32_e32 v204, v173, v204
	v_cvt_pk_bf16_f32 v165, v165, v175
	s_waitcnt lgkmcnt(4)
	v_mfma_f32_32x32x16_bf16 v[80:95], v[250:253], v[126:129], v[80:95]
	ds_read_b128 v[250:253], v193 offset:49152
	v_exp_f32_e32 v150, v150
	v_add_f32_e32 v204, v167, v204
	v_add_f32_e32 v204, v174, v204
	v_cvt_pk_bf16_f32 v166, v166, v173
	v_mfma_f32_32x32x16_bf16 v[64:79], v[244:247], v[126:129], v[64:79]
	ds_read_b128 v[244:247], v193 offset:57344
	v_exp_f32_e32 v151, v151
	v_add_f32_e32 v204, v168, v204
	v_add_f32_e32 v204, v171, v204
	v_cvt_pk_bf16_f32 v167, v167, v174
	s_waitcnt lgkmcnt(4)
	v_mfma_f32_32x32x16_bf16 v[80:95], v[212:215], v[122:125], v[80:95]
	ds_read_b128 v[212:215], v202 offset:49152
	v_exp_f32_e32 v148, v148
	v_add_f32_e32 v204, v169, v204
	v_add_f32_e32 v204, v172, v204
	v_cvt_pk_bf16_f32 v168, v168, v171
	v_mfma_f32_32x32x16_bf16 v[64:79], v[216:219], v[122:125], v[64:79]
	ds_read_b128 v[216:219], v202 offset:57344
	v_exp_f32_e32 v149, v149
	v_add_f32_e32 v204, v160, v204
	v_add_f32_e32 v204, v161, v204
	v_cvt_pk_bf16_f32 v169, v169, v172
	s_waitcnt lgkmcnt(4)
	v_mfma_f32_32x32x16_bf16 v[80:95], v[232:235], v[110:113], v[80:95]
	ds_read_b128 v[232:235], v201 offset:49152
	v_exp_f32_e32 v156, v156
	v_add_f32_e32 v204, v158, v204
	v_add_f32_e32 v204, v159, v204
	v_cvt_pk_bf16_f32 v172, v160, v161
	v_mfma_f32_32x32x16_bf16 v[64:79], v[236:239], v[110:113], v[64:79]
	ds_read_b128 v[236:239], v201 offset:57344
	v_exp_f32_e32 v157, v157
	v_add_f32_e32 v204, v154, v204
	v_add_f32_e32 v204, v155, v204
	v_cvt_pk_bf16_f32 v173, v158, v159
	s_waitcnt lgkmcnt(4)
	v_mfma_f32_32x32x16_bf16 v[80:95], v[250:253], v[106:109], v[80:95]
	v_exp_f32_e32 v152, v152
	v_add_f32_e32 v204, v150, v204
	v_add_f32_e32 v204, v151, v204
	v_cvt_pk_bf16_f32 v174, v154, v155
	v_mfma_f32_32x32x16_bf16 v[64:79], v[244:247], v[106:109], v[64:79]
	v_exp_f32_e32 v153, v153
	v_add_f32_e32 v204, v148, v204
	v_add_f32_e32 v204, v149, v204
	v_cvt_pk_bf16_f32 v175, v150, v151
	s_waitcnt lgkmcnt(2)
	v_mfma_f32_32x32x16_bf16 v[80:95], v[212:215], v[102:105], v[80:95]
	v_exp_f32_e32 v146, v146
	v_add_f32_e32 v204, v156, v204
	v_add_f32_e32 v204, v157, v204
	v_cvt_pk_bf16_f32 v206, v148, v149
	v_mfma_f32_32x32x16_bf16 v[64:79], v[216:219], v[102:105], v[64:79]
	v_exp_f32_e32 v147, v147
	v_add_f32_e32 v204, v152, v204
	v_add_f32_e32 v204, v153, v204
	v_cvt_pk_bf16_f32 v207, v156, v157
	ds_read_b64_tr_b16 v[210:211], v187 offset:0x0
	ds_read_b64_tr_b16 v[212:213], v187 offset:0x800
	ds_read_b64_tr_b16 v[214:215], v187 offset:0x200
	ds_read_b64_tr_b16 v[216:217], v187 offset:0xa00
	ds_read_b64_tr_b16 v[218:219], v187 offset:0x400
	ds_read_b64_tr_b16 v[220:221], v187 offset:0xc00
	ds_read_b64_tr_b16 v[222:223], v187 offset:0x600
	ds_read_b64_tr_b16 v[224:225], v187 offset:0xe00
	s_waitcnt lgkmcnt(8)
	v_mfma_f32_32x32x16_bf16 v[80:95], v[232:235], v[98:101], v[80:95]
	v_add_f32_e32 v204, v146, v204
	v_add_f32_e32 v204, v147, v204
	v_mov_b32_e32 v205, v204
	v_cvt_pk_bf16_f32 v208, v152, v153
	v_mfma_f32_32x32x16_bf16 v[64:79], v[236:239], v[98:101], v[64:79]
	s_nop 0
	v_permlane32_swap_b32_e32 v204, v205
	v_cvt_pk_bf16_f32 v209, v146, v147
	s_waitcnt vmcnt(0)
	ds_write_b128 v188, v[134:137] offset:32768
	ds_write_b128 v189, v[142:145] offset:32768
	global_load_dwordx4 v[146:149], v178, s[66:67]
	global_load_dwordx4 v[150:153], v179, s[66:67]
	global_load_dwordx4 v[154:157], v178, s[98:99]
	global_load_dwordx4 v[158:161], v179, s[98:99]
	s_add_u32 s66, s66, 0x4000
	s_addc_u32 s67, s67, 0
	s_add_u32 s98, s98, 0x4000
	s_addc_u32 s99, s99, 0
	s_waitcnt lgkmcnt(6)
	v_mfma_f32_32x32x16_bf16 v[0:15], v[162:165], v[210:213], v[0:15]
	ds_read_b64_tr_b16 v[210:211], v187 offset:0x1000
	ds_read_b64_tr_b16 v[212:213], v187 offset:0x1800
	v_max_f32_e32 v240, v80, v81
	v_max3_f32 v240, v240, v82, v83
	v_max3_f32 v240, v240, v84, v85
	v_max3_f32 v240, v240, v86, v87
	v_max3_f32 v240, v240, v88, v89
	v_mfma_f32_32x32x16_bf16 v[48:63], v[162:165], v[214:217], v[48:63]
	ds_read_b64_tr_b16 v[214:215], v187 offset:0x1200
	ds_read_b64_tr_b16 v[216:217], v187 offset:0x1a00
	v_max3_f32 v240, v240, v90, v91
	v_max3_f32 v240, v240, v92, v93
	v_max3_f32 v240, v240, v94, v95
	v_max3_f32 v240, v240, v64, v65
	v_max3_f32 v240, v240, v66, v67
	v_max3_f32 v240, v240, v68, v69
	s_waitcnt lgkmcnt(6)
	v_mfma_f32_32x32x16_bf16 v[32:47], v[162:165], v[218:221], v[32:47]
	ds_read_b64_tr_b16 v[218:219], v187 offset:0x1400
	ds_read_b64_tr_b16 v[220:221], v187 offset:0x1c00
	v_max3_f32 v240, v240, v70, v71
	v_max3_f32 v240, v240, v72, v73
	v_max3_f32 v240, v240, v74, v75
	v_max3_f32 v240, v240, v76, v77
	v_max3_f32 v240, v240, v78, v79
	v_mfma_f32_32x32x16_bf16 v[16:31], v[162:165], v[222:225], v[16:31]
	ds_read_b64_tr_b16 v[222:223], v187 offset:0x1600
	ds_read_b64_tr_b16 v[224:225], v187 offset:0x1e00
	v_mov_b32_e32 v241, v240
	s_nop 1
	v_permlane32_swap_b32_e32 v240, v241
	v_max_f32_e32 v240, v240, v241
	v_sub_f32_e32 v241, v240, v243
	v_cmp_ge_f32_e32 vcc, s92, v241
	s_waitcnt lgkmcnt(4)
	v_mfma_f32_32x32x16_bf16 v[0:15], v[166:169], v[210:213], v[0:15]
	ds_read_b64_tr_b16 v[210:211], v187 offset:0x2000
	ds_read_b64_tr_b16 v[212:213], v187 offset:0x2800
	s_cmp_eq_u64 vcc, exec
	s_cselect_b64 s[42:43], -1, 0
	s_cbranch_scc1 .Lattn_common_a
	v_max_f32_e32 v240, v243, v240
	v_sub_f32_e32 v241, v243, v240
	v_mul_f32_e32 v241, 0x3e0293ee, v241
	v_exp_f32_e32 v241, v241
	v_mov_b32_e32 v243, v240
	v_mul_f32_e32 v242, 0xbe0293ee, v243
.Lattn_common_a:
	v_mfma_f32_32x32x16_bf16 v[48:63], v[166:169], v[214:217], v[48:63]
	ds_read_b64_tr_b16 v[214:215], v187 offset:0x2200
	ds_read_b64_tr_b16 v[216:217], v187 offset:0x2a00
	v_fmamk_f32 v80, v80, 0x3e0293ee, v242
	v_fmamk_f32 v81, v81, 0x3e0293ee, v242
	v_fmamk_f32 v82, v82, 0x3e0293ee, v242
	v_fmamk_f32 v83, v83, 0x3e0293ee, v242
	s_waitcnt lgkmcnt(4)
	v_mfma_f32_32x32x16_bf16 v[32:47], v[166:169], v[218:221], v[32:47]
	ds_read_b64_tr_b16 v[218:219], v187 offset:0x2400
	ds_read_b64_tr_b16 v[220:221], v187 offset:0x2c00
	v_fmamk_f32 v84, v84, 0x3e0293ee, v242
	v_fmamk_f32 v85, v85, 0x3e0293ee, v242
	v_fmamk_f32 v86, v86, 0x3e0293ee, v242
	v_fmamk_f32 v87, v87, 0x3e0293ee, v242
	v_fmamk_f32 v88, v88, 0x3e0293ee, v242
	v_fmamk_f32 v89, v89, 0x3e0293ee, v242
	v_mfma_f32_32x32x16_bf16 v[16:31], v[166:169], v[222:225], v[16:31]
	ds_read_b64_tr_b16 v[222:223], v187 offset:0x2600
	ds_read_b64_tr_b16 v[224:225], v187 offset:0x2e00
	v_fmamk_f32 v90, v90, 0x3e0293ee, v242
	v_fmamk_f32 v91, v91, 0x3e0293ee, v242
	v_fmamk_f32 v92, v92, 0x3e0293ee, v242
	v_fmamk_f32 v93, v93, 0x3e0293ee, v242
	v_fmamk_f32 v94, v94, 0x3e0293ee, v242
	v_fmamk_f32 v95, v95, 0x3e0293ee, v242
	s_waitcnt lgkmcnt(4)
	v_mfma_f32_32x32x16_bf16 v[0:15], v[172:175], v[210:213], v[0:15]
	ds_read_b64_tr_b16 v[210:211], v187 offset:0x3000
	ds_read_b64_tr_b16 v[212:213], v187 offset:0x3800
	v_exp_f32_e32 v177, v81
	v_exp_f32_e32 v176, v83
	v_mfma_f32_32x32x16_bf16 v[48:63], v[172:175], v[214:217], v[48:63]
	ds_read_b64_tr_b16 v[214:215], v187 offset:0x3200
	ds_read_b64_tr_b16 v[216:217], v187 offset:0x3a00
	v_exp_f32_e32 v171, v93
	v_exp_f32_e32 v170, v95
	s_waitcnt lgkmcnt(4)
	v_mfma_f32_32x32x16_bf16 v[32:47], v[172:175], v[218:221], v[32:47]
	ds_read_b64_tr_b16 v[218:219], v187 offset:0x3400
	ds_read_b64_tr_b16 v[220:221], v187 offset:0x3c00
	v_exp_f32_e32 v162, v80
	v_exp_f32_e32 v163, v82
	v_mfma_f32_32x32x16_bf16 v[16:31], v[172:175], v[222:225], v[16:31]
	ds_read_b64_tr_b16 v[222:223], v187 offset:0x3600
	ds_read_b64_tr_b16 v[224:225], v187 offset:0x3e00
	v_exp_f32_e32 v164, v84
	v_exp_f32_e32 v165, v86
	s_waitcnt lgkmcnt(4)
	v_mfma_f32_32x32x16_bf16 v[0:15], v[206:209], v[210:213], v[0:15]
	v_exp_f32_e32 v166, v88
	v_exp_f32_e32 v167, v90
	v_mfma_f32_32x32x16_bf16 v[48:63], v[206:209], v[214:217], v[48:63]
	v_exp_f32_e32 v168, v92
	v_exp_f32_e32 v169, v94
	s_waitcnt lgkmcnt(0)
	v_mfma_f32_32x32x16_bf16 v[32:47], v[206:209], v[218:221], v[32:47]
	v_exp_f32_e32 v175, v85
	v_exp_f32_e32 v174, v87
	v_mfma_f32_32x32x16_bf16 v[16:31], v[206:209], v[222:225], v[16:31]
	v_exp_f32_e32 v173, v89
	v_exp_f32_e32 v172, v91
	s_barrier
	v_cndmask_b32_e64 v206, v241, 1.0, s[42:43]
	ds_write_b128 v190, v[130:133]
	ds_write_b128 v191, v[138:141]
	s_cmp_lg_u64 s[42:43], 0
	s_cbranch_scc1 .LBB0_530
	s_and_saveexec_b64 s[6:7], s[40:41]
	ds_write_b32 v184, v206 offset:128
	s_or_b64 exec, exec, s[6:7]
	s_waitcnt lgkmcnt(0)
	ds_read_b128 v[210:213], v182 offset:224
	ds_read_b128 v[214:217], v182 offset:192
	ds_read_b128 v[218:221], v182 offset:160
	ds_read_b128 v[222:225], v182 offset:128
	s_waitcnt lgkmcnt(3)
	v_pk_mul_f32 v[14:15], v[14:15], v[212:213]
	s_waitcnt lgkmcnt(2)
	v_pk_mul_f32 v[10:11], v[10:11], v[216:217]
	s_waitcnt lgkmcnt(1)
	v_pk_mul_f32 v[6:7], v[6:7], v[220:221]
	s_waitcnt lgkmcnt(0)
	v_pk_mul_f32 v[2:3], v[2:3], v[224:225]
	v_pk_mul_f32 v[12:13], v[12:13], v[210:211]
	v_pk_mul_f32 v[8:9], v[8:9], v[214:215]
	v_pk_mul_f32 v[4:5], v[4:5], v[218:219]
	v_pk_mul_f32 v[0:1], v[0:1], v[222:223]
	v_pk_mul_f32 v[62:63], v[62:63], v[212:213]
	v_pk_mul_f32 v[58:59], v[58:59], v[216:217]
	v_pk_mul_f32 v[54:55], v[54:55], v[220:221]
	v_pk_mul_f32 v[50:51], v[50:51], v[224:225]
	v_pk_mul_f32 v[60:61], v[60:61], v[210:211]
	v_pk_mul_f32 v[56:57], v[56:57], v[214:215]
	v_pk_mul_f32 v[52:53], v[52:53], v[218:219]
	v_pk_mul_f32 v[48:49], v[48:49], v[222:223]
	v_pk_mul_f32 v[46:47], v[46:47], v[212:213]
	v_pk_mul_f32 v[42:43], v[42:43], v[216:217]
	v_pk_mul_f32 v[38:39], v[38:39], v[220:221]
	v_pk_mul_f32 v[34:35], v[34:35], v[224:225]
	v_pk_mul_f32 v[44:45], v[44:45], v[210:211]
	v_pk_mul_f32 v[40:41], v[40:41], v[214:215]
	v_pk_mul_f32 v[36:37], v[36:37], v[218:219]
	v_pk_mul_f32 v[32:33], v[32:33], v[222:223]
	v_pk_mul_f32 v[30:31], v[30:31], v[212:213]
	v_pk_mul_f32 v[26:27], v[26:27], v[216:217]
	v_pk_mul_f32 v[22:23], v[22:23], v[220:221]
	v_pk_mul_f32 v[18:19], v[18:19], v[224:225]
	v_pk_mul_f32 v[28:29], v[28:29], v[210:211]
	v_pk_mul_f32 v[24:25], v[24:25], v[214:215]
	v_pk_mul_f32 v[20:21], v[20:21], v[218:219]
	v_pk_mul_f32 v[16:17], v[16:17], v[222:223]
.LBB0_530:
	v_fmamk_f32 v217, v64, 0x3e0293ee, v242
	v_fmamk_f32 v218, v65, 0x3e0293ee, v242
	v_fmamk_f32 v219, v66, 0x3e0293ee, v242
	v_fmamk_f32 v220, v67, 0x3e0293ee, v242
	v_fmamk_f32 v221, v68, 0x3e0293ee, v242
	v_fmamk_f32 v210, v69, 0x3e0293ee, v242
	v_fmamk_f32 v211, v70, 0x3e0293ee, v242
	v_fmamk_f32 v212, v71, 0x3e0293ee, v242
	v_fmamk_f32 v213, v72, 0x3e0293ee, v242
	v_fmamk_f32 v214, v73, 0x3e0293ee, v242
	v_fmamk_f32 v215, v74, 0x3e0293ee, v242
	v_fmamk_f32 v216, v75, 0x3e0293ee, v242
	v_fmamk_f32 v209, v76, 0x3e0293ee, v242
	v_fmamk_f32 v222, v77, 0x3e0293ee, v242
	v_fmamk_f32 v223, v78, 0x3e0293ee, v242
	v_fmamk_f32 v208, v79, 0x3e0293ee, v242
	s_waitcnt lgkmcnt(0)
	s_barrier
	ds_read_b128 v[64:67], v192 offset:32768
	ds_read_b128 v[68:71], v192 offset:40960
	ds_read_b128 v[232:235], v200 offset:32768
	ds_read_b128 v[236:239], v200 offset:40960
	ds_read_b128 v[250:253], v199 offset:32768
	ds_read_b128 v[244:247], v199 offset:40960
	ds_read_b128 v[224:227], v198 offset:32768
	ds_read_b128 v[228:231], v198 offset:40960
	v_exp_f32_e32 v248, v208
	v_exp_f32_e32 v249, v209
	v_add_f32_e32 v208, v162, v177
	s_waitcnt lgkmcnt(6)
	v_mfma_f32_32x32x16_bf16 v[80:95], v[64:67], v[118:121], 0
	v_exp_f32_e32 v217, v217
	v_add_f32_e32 v208, v163, v208
	v_add_f32_e32 v208, v176, v208
	v_cvt_pk_bf16_f32 v162, v162, v177
	v_mfma_f32_32x32x16_bf16 v[64:79], v[68:71], v[118:121], 0
	v_exp_f32_e32 v218, v218
	v_add_f32_e32 v208, v164, v208
	v_add_f32_e32 v208, v175, v208
	v_cvt_pk_bf16_f32 v163, v163, v176
	s_waitcnt lgkmcnt(4)
	v_mfma_f32_32x32x16_bf16 v[80:95], v[232:235], v[114:117], v[80:95]
	ds_read_b128 v[232:235], v195 offset:32768
	v_exp_f32_e32 v219, v219
	v_add_f32_e32 v208, v165, v208
	v_add_f32_e32 v208, v174, v208
	v_cvt_pk_bf16_f32 v164, v164, v175
	v_mfma_f32_32x32x16_bf16 v[64:79], v[236:239], v[114:117], v[64:79]
	ds_read_b128 v[236:239], v195 offset:40960
	v_exp_f32_e32 v220, v220
	v_add_f32_e32 v208, v166, v208
	v_add_f32_e32 v208, v173, v208
	v_cvt_pk_bf16_f32 v165, v165, v174
	s_waitcnt lgkmcnt(4)
	v_mfma_f32_32x32x16_bf16 v[80:95], v[250:253], v[126:129], v[80:95]
	ds_read_b128 v[250:253], v193 offset:32768
	v_exp_f32_e32 v221, v221
	v_add_f32_e32 v208, v167, v208
	v_add_f32_e32 v208, v172, v208
	v_cvt_pk_bf16_f32 v166, v166, v173
	v_mfma_f32_32x32x16_bf16 v[64:79], v[244:247], v[126:129], v[64:79]
	ds_read_b128 v[244:247], v193 offset:40960
	v_exp_f32_e32 v210, v210
	v_add_f32_e32 v208, v168, v208
	v_add_f32_e32 v208, v171, v208
	v_cvt_pk_bf16_f32 v167, v167, v172
	s_waitcnt lgkmcnt(4)
	v_mfma_f32_32x32x16_bf16 v[80:95], v[224:227], v[122:125], v[80:95]
	ds_read_b128 v[224:227], v202 offset:32768
	v_exp_f32_e32 v211, v211
	v_add_f32_e32 v208, v169, v208
	v_add_f32_e32 v208, v170, v208
	v_cvt_pk_bf16_f32 v168, v168, v171
	v_mfma_f32_32x32x16_bf16 v[64:79], v[228:231], v[122:125], v[64:79]
	ds_read_b128 v[228:231], v202 offset:40960
	v_exp_f32_e32 v212, v212
	v_add_f32_e32 v208, v217, v208
	v_add_f32_e32 v208, v218, v208
	v_cvt_pk_bf16_f32 v169, v169, v170
	s_waitcnt lgkmcnt(4)
	v_mfma_f32_32x32x16_bf16 v[80:95], v[232:235], v[110:113], v[80:95]
	ds_read_b128 v[232:235], v201 offset:32768
	v_exp_f32_e32 v213, v213
	v_add_f32_e32 v208, v219, v208
	v_add_f32_e32 v208, v220, v208
	v_cvt_pk_bf16_f32 v170, v217, v218
	v_mfma_f32_32x32x16_bf16 v[64:79], v[236:239], v[110:113], v[64:79]
	ds_read_b128 v[236:239], v201 offset:40960
	v_exp_f32_e32 v214, v214
	v_add_f32_e32 v208, v221, v208
	v_add_f32_e32 v208, v210, v208
	v_cvt_pk_bf16_f32 v171, v219, v220
	s_waitcnt lgkmcnt(4)
	v_mfma_f32_32x32x16_bf16 v[80:95], v[250:253], v[106:109], v[80:95]
	v_exp_f32_e32 v215, v215
	v_add_f32_e32 v208, v211, v208
	v_add_f32_e32 v208, v212, v208
	v_cvt_pk_bf16_f32 v172, v221, v210
	v_mfma_f32_32x32x16_bf16 v[64:79], v[244:247], v[106:109], v[64:79]
	v_exp_f32_e32 v216, v216
	v_add_f32_e32 v208, v213, v208
	v_add_f32_e32 v208, v214, v208
	v_cvt_pk_bf16_f32 v173, v211, v212
	s_waitcnt lgkmcnt(2)
	v_mfma_f32_32x32x16_bf16 v[80:95], v[224:227], v[102:105], v[80:95]
	v_exp_f32_e32 v222, v222
	v_add_f32_e32 v208, v215, v208
	v_add_f32_e32 v208, v216, v208
	v_cvt_pk_bf16_f32 v174, v213, v214
	v_mfma_f32_32x32x16_bf16 v[64:79], v[228:231], v[102:105], v[64:79]
	v_exp_f32_e32 v223, v223
	v_add_f32_e32 v208, v249, v208
	v_add_f32_e32 v208, v222, v208
	v_cvt_pk_bf16_f32 v175, v215, v216
	s_waitcnt lgkmcnt(0)
	v_mfma_f32_32x32x16_bf16 v[80:95], v[232:235], v[98:101], v[80:95]
	v_add_f32_e32 v208, v223, v208
	v_add_f32_e32 v208, v248, v208
	v_mov_b32_e32 v209, v208
	v_cvt_pk_bf16_f32 v176, v249, v222
	v_mfma_f32_32x32x16_bf16 v[64:79], v[236:239], v[98:101], v[64:79]
	v_cvt_pk_bf16_f32 v177, v223, v248
	ds_read_b64_tr_b16 v[210:211], v186 offset:0x0
	ds_read_b64_tr_b16 v[212:213], v186 offset:0x800
	ds_read_b64_tr_b16 v[214:215], v186 offset:0x200
	ds_read_b64_tr_b16 v[216:217], v186 offset:0xa00
	ds_read_b64_tr_b16 v[218:219], v186 offset:0x400
	ds_read_b64_tr_b16 v[220:221], v186 offset:0xc00
	ds_read_b64_tr_b16 v[222:223], v186 offset:0x600
	ds_read_b64_tr_b16 v[224:225], v186 offset:0xe00
	s_nop 1
	v_permlane32_swap_b32_e32 v208, v209
	s_waitcnt vmcnt(1)
	ds_write_b128 v188, v[154:157] offset:49152
	s_waitcnt vmcnt(0)
	ds_write_b128 v189, v[158:161] offset:49152
	s_cmp_ge_u32 s34, s35
	s_cselect_b64 s[6:7], -1, 0
	s_cbranch_scc1 .LBB0_532
	global_load_dwordx4 v[130:133], v178, s[66:67]
	global_load_dwordx4 v[134:137], v178, s[98:99]
	global_load_dwordx4 v[138:141], v179, s[66:67]
	global_load_dwordx4 v[142:145], v179, s[98:99]
	s_add_u32 s66, s66, 0x4000
	s_addc_u32 s67, s67, 0
	s_add_u32 s98, s98, 0x4000
	s_addc_u32 s99, s99, 0

.Lattn_common_b:
	v_mfma_f32_32x32x16_bf16 v[48:63], v[166:169], v[214:217], v[48:63]
	ds_read_b64_tr_b16 v[214:215], v186 offset:0x2200
	ds_read_b64_tr_b16 v[216:217], v186 offset:0x2a00
	v_fmamk_f32 v80, v80, 0x3e0293ee, v242
	v_fmamk_f32 v81, v81, 0x3e0293ee, v242
	v_fmamk_f32 v82, v82, 0x3e0293ee, v242
	v_fmamk_f32 v83, v83, 0x3e0293ee, v242
	s_waitcnt lgkmcnt(4)
	v_mfma_f32_32x32x16_bf16 v[32:47], v[166:169], v[218:221], v[32:47]
	ds_read_b64_tr_b16 v[218:219], v186 offset:0x2400
	ds_read_b64_tr_b16 v[220:221], v186 offset:0x2c00
	v_fmamk_f32 v84, v84, 0x3e0293ee, v242
	v_fmamk_f32 v85, v85, 0x3e0293ee, v242
	v_fmamk_f32 v86, v86, 0x3e0293ee, v242
	v_fmamk_f32 v87, v87, 0x3e0293ee, v242
	v_fmamk_f32 v88, v88, 0x3e0293ee, v242
	v_fmamk_f32 v89, v89, 0x3e0293ee, v242
	v_mfma_f32_32x32x16_bf16 v[16:31], v[166:169], v[222:225], v[16:31]
	ds_read_b64_tr_b16 v[222:223], v186 offset:0x2600
	ds_read_b64_tr_b16 v[224:225], v186 offset:0x2e00
	v_fmamk_f32 v90, v90, 0x3e0293ee, v242
	v_fmamk_f32 v91, v91, 0x3e0293ee, v242
	v_fmamk_f32 v92, v92, 0x3e0293ee, v242
	v_fmamk_f32 v93, v93, 0x3e0293ee, v242
	v_fmamk_f32 v94, v94, 0x3e0293ee, v242
	v_fmamk_f32 v95, v95, 0x3e0293ee, v242
	s_waitcnt lgkmcnt(4)
	v_mfma_f32_32x32x16_bf16 v[0:15], v[170:173], v[210:213], v[0:15]
	ds_read_b64_tr_b16 v[210:211], v186 offset:0x3000
	ds_read_b64_tr_b16 v[212:213], v186 offset:0x3800
	v_exp_f32_e32 v207, v83
	v_exp_f32_e32 v163, v80
	v_mfma_f32_32x32x16_bf16 v[48:63], v[170:173], v[214:217], v[48:63]
	ds_read_b64_tr_b16 v[214:215], v186 offset:0x3200
	ds_read_b64_tr_b16 v[216:217], v186 offset:0x3a00
	v_exp_f32_e32 v164, v82
	v_exp_f32_e32 v165, v86
	s_waitcnt lgkmcnt(4)
	v_mfma_f32_32x32x16_bf16 v[32:47], v[170:173], v[218:221], v[32:47]
	ds_read_b64_tr_b16 v[218:219], v186 offset:0x3400
	ds_read_b64_tr_b16 v[220:221], v186 offset:0x3c00
	v_exp_f32_e32 v166, v88
	v_exp_f32_e32 v167, v90
	v_mfma_f32_32x32x16_bf16 v[16:31], v[170:173], v[222:225], v[16:31]
	ds_read_b64_tr_b16 v[222:223], v186 offset:0x3600
	ds_read_b64_tr_b16 v[224:225], v186 offset:0x3e00
	v_exp_f32_e32 v168, v92
	v_exp_f32_e32 v169, v94
	s_waitcnt lgkmcnt(4)
	v_mfma_f32_32x32x16_bf16 v[0:15], v[174:177], v[210:213], v[0:15]
	v_exp_f32_e32 v171, v93
	v_exp_f32_e32 v172, v95
	v_mfma_f32_32x32x16_bf16 v[48:63], v[174:177], v[214:217], v[48:63]
	v_exp_f32_e32 v173, v89
	v_exp_f32_e32 v210, v85
	s_waitcnt lgkmcnt(0)
	v_mfma_f32_32x32x16_bf16 v[32:47], v[174:177], v[218:221], v[32:47]
	v_mfma_f32_32x32x16_bf16 v[16:31], v[174:177], v[222:225], v[16:31]
	v_exp_f32_e32 v174, v91
	v_exp_f32_e32 v175, v87
	v_exp_f32_e32 v176, v84
	v_exp_f32_e32 v177, v81
	s_barrier
	v_cndmask_b32_e64 v162, v241, 1.0, s[42:43]
	ds_write_b128 v190, v[146:149] offset:16384
	ds_write_b128 v191, v[150:153] offset:16384
	s_cmp_lg_u64 s[42:43], 0
	s_cbranch_scc1 .LBB0_536
	s_and_saveexec_b64 s[8:9], s[40:41]
	ds_write_b32 v184, v162 offset:128
	s_or_b64 exec, exec, s[8:9]
	s_waitcnt lgkmcnt(0)
	ds_read_b128 v[146:149], v182 offset:224
	ds_read_b128 v[150:153], v182 offset:192
	ds_read_b128 v[154:157], v182 offset:160
	ds_read_b128 v[158:161], v182 offset:128
	s_waitcnt lgkmcnt(3)
	v_pk_mul_f32 v[14:15], v[14:15], v[148:149]
	s_waitcnt lgkmcnt(2)
	v_pk_mul_f32 v[10:11], v[10:11], v[152:153]
	s_waitcnt lgkmcnt(1)
	v_pk_mul_f32 v[6:7], v[6:7], v[156:157]
	s_waitcnt lgkmcnt(0)
	v_pk_mul_f32 v[2:3], v[2:3], v[160:161]
	v_pk_mul_f32 v[12:13], v[12:13], v[146:147]
	v_pk_mul_f32 v[8:9], v[8:9], v[150:151]
	v_pk_mul_f32 v[4:5], v[4:5], v[154:155]
	v_pk_mul_f32 v[0:1], v[0:1], v[158:159]
	v_pk_mul_f32 v[62:63], v[62:63], v[148:149]
	v_pk_mul_f32 v[58:59], v[58:59], v[152:153]
	v_pk_mul_f32 v[54:55], v[54:55], v[156:157]
	v_pk_mul_f32 v[50:51], v[50:51], v[160:161]
	v_pk_mul_f32 v[60:61], v[60:61], v[146:147]
	v_pk_mul_f32 v[56:57], v[56:57], v[150:151]
	v_pk_mul_f32 v[52:53], v[52:53], v[154:155]
	v_pk_mul_f32 v[48:49], v[48:49], v[158:159]
	v_pk_mul_f32 v[46:47], v[46:47], v[148:149]
	v_pk_mul_f32 v[42:43], v[42:43], v[152:153]
	v_pk_mul_f32 v[38:39], v[38:39], v[156:157]
	v_pk_mul_f32 v[34:35], v[34:35], v[160:161]
	v_pk_mul_f32 v[44:45], v[44:45], v[146:147]
	v_pk_mul_f32 v[40:41], v[40:41], v[150:151]
	v_pk_mul_f32 v[36:37], v[36:37], v[154:155]
	v_pk_mul_f32 v[32:33], v[32:33], v[158:159]
	v_pk_mul_f32 v[30:31], v[30:31], v[148:149]
	v_pk_mul_f32 v[26:27], v[26:27], v[152:153]
	v_pk_mul_f32 v[22:23], v[22:23], v[156:157]
	v_pk_mul_f32 v[18:19], v[18:19], v[160:161]
	v_pk_mul_f32 v[28:29], v[28:29], v[146:147]
	v_pk_mul_f32 v[24:25], v[24:25], v[150:151]
	v_pk_mul_f32 v[20:21], v[20:21], v[154:155]
	v_pk_mul_f32 v[16:17], v[16:17], v[158:159]
